# XCD-aware permutation extended to the partial last round of mixers items (ctx position-DFT tiles) + pipelined DFT K-loops, on top of v32
# baseline (speedup 1.0000x reference)
.LBB0_595:
	s_mov_b32 s33, s100
	s_cmpk_gt_u32 s100, 0xbff
	s_cbranch_scc1 .Lxcd_tail
	s_and_b32 s33, s100, 7
	s_lshl_b32 s33, s33, 6
	s_bfe_u32 s2, s100, 0x60003
	s_or_b32 s33, s33, s2
	s_and_b32 s2, s100, 0xfffffe00
	s_or_b32 s33, s33, s2
	s_branch .Lxcd_done
.Lxcd_tail:
	s_and_b32 s33, s100, 7
	s_lshl_b32 s33, s33, 5
	s_bfe_u32 s2, s100, 0x50003
	s_or_b32 s33, s33, s2
	s_or_b32 s33, s33, 0xc00
